# combo15 = combo14 + own-block causal tile: waves 0-3 skip the fully masked second key half (exact no-op removal)
# speedup vs baseline: 1.0123x; 1.0031x over previous
; __device__ __forceinline__ void stage_kv_load(u32x4 (&kr)[8], u32x4 (&vr)[8], const bf16_t* Kg, int kpitch, const bf16_t* Vtg, int tid) {
; #pragma unroll
;     for (int i = 0; i < 8; ++i) { const int c = tid + 512 * i, row = c >> 4, ch = c & 15; kr[i] = *(const u32x4*)(Kg + (size_t)row * kpitch + ch * 8); }
; #pragma unroll
;     for (int i = 0; i < 8; ++i) { const int c = tid + 512 * i, row = c >> 5, ch = c & 31; vr[i] = *(const u32x4*)(Vtg + (size_t)row * 256 + ch * 8); }
; }
; __global__ void __launch_bounds__(512, 2) mk_fwd(Args a) {
;     ...
;                     const int h = it & 7, b = it >> 3;
;                     u32x4 kr[8], vr[8];
;                     stage_kv_load(kr, vr, PROJ + (size_t)(256 * b) * INW + 1024 + 128 * h, INW, VT + (size_t)(h * 64 + b) * 128 * 256, tid);
;                     const int qi = 32 * wave + r32, tok = 256 * b + qi;
;                     const bf16_t* qrow = PROJ + (size_t)tok * INW + 128 * h + 8 * hi;
;                     bf16x8 qf[8];
; #pragma unroll
;                     for (int d0 = 0; d0 < 8; ++d0) qf[d0] = *(const bf16x8*)(qrow + 16 * d0);
.LBB0_22:
	s_ashr_i32 s14, s7, 3
	s_and_b32 s15, s7, 7
	s_lshl_b32 s18, s14, 8
	s_mul_i32 s0, s14, 0x280000
	s_mul_hi_i32 s1, s18, 0x2800
	s_add_u32 s0, s72, s0
	v_mov_b32_e32 v163, v232
	s_addc_u32 s1, s73, s1
	s_lshl_b32 s20, s15, 7
	s_lshl_b32 s74, s15, 8
	s_add_u32 s0, s0, s74
	v_lshlrev_b32_e32 v32, 4, v163
	s_addc_u32 s1, s1, 0
	s_lshl_b32 s15, s15, 6
	v_and_b32_e32 v128, 0xf0, v32
	v_add_u32_e32 v34, 0x200, v163
	s_add_i32 s16, s15, s14
	v_lshl_add_u64 v[24:25], s[0:1], 0, v[128:129]
	v_ashrrev_i32_e32 v86, 4, v163
	s_movk_i32 s15, 0x2800
	v_ashrrev_i32_e32 v88, 4, v34
	s_waitcnt lgkmcnt(0)
	v_mad_i64_i32 v[0:1], s[0:1], v86, s15, v[24:25]
	v_mad_i64_i32 v[4:5], s[0:1], v88, s15, v[24:25]
	v_add_u32_e32 v40, 0x400, v163
	v_add_u32_e32 v42, 0x600, v163
	flat_load_dwordx4 v[0:3], v[0:1] offset:2048
	s_nop 0
	flat_load_dwordx4 v[4:7], v[4:5] offset:2048
	v_ashrrev_i32_e32 v89, 4, v40
	v_ashrrev_i32_e32 v90, 4, v42
	v_mad_i64_i32 v[8:9], s[0:1], v89, s15, v[24:25]
	v_mad_i64_i32 v[12:13], s[0:1], v90, s15, v[24:25]
	v_add_u32_e32 v48, 0x800, v163
	v_add_u32_e32 v50, 0xa00, v163
	flat_load_dwordx4 v[8:11], v[8:9] offset:2048
	s_nop 0
	flat_load_dwordx4 v[12:15], v[12:13] offset:2048
	v_ashrrev_i32_e32 v91, 4, v48
	v_ashrrev_i32_e32 v92, 4, v50
	s_ashr_i32 s17, s16, 31
	v_mad_i64_i32 v[16:17], s[0:1], v91, s15, v[24:25]
	v_mad_i64_i32 v[20:21], s[0:1], v92, s15, v[24:25]
	v_add_u32_e32 v56, 0xc00, v163
	v_add_u32_e32 v62, 0xe00, v163
	s_lshl_b64 s[16:17], s[16:17], 16
	flat_load_dwordx4 v[16:19], v[16:17] offset:2048
	s_nop 0
	flat_load_dwordx4 v[20:23], v[20:21] offset:2048
	v_ashrrev_i32_e32 v93, 4, v56
	v_ashrrev_i32_e32 v94, 4, v62
	s_add_u32 s16, s96, s16
	v_mad_i64_i32 v[26:27], s[0:1], v93, s15, v[24:25]
	v_mad_i64_i32 v[28:29], s[0:1], v94, s15, v[24:25]
	v_ashrrev_i32_e32 v66, 5, v163
	v_ashrrev_i32_e32 v68, 5, v34
	s_addc_u32 s17, s97, s17
	flat_load_dwordx4 v[24:27], v[26:27] offset:2048
	s_nop 0
	flat_load_dwordx4 v[28:31], v[28:29] offset:2048
	v_and_b32_e32 v64, 0x1f0, v32
	v_mov_b32_e32 v65, v129
	v_ashrrev_i32_e32 v67, 31, v66
	v_ashrrev_i32_e32 v69, 31, v68
	v_readfirstlane_b32 s0, v163
	v_lshl_add_u64 v[60:61], s[16:17], 0, v[64:65]
	v_lshlrev_b64 v[32:33], 9, v[66:67]
	v_lshlrev_b64 v[34:35], 9, v[68:69]
	v_ashrrev_i32_e32 v70, 5, v40
	v_ashrrev_i32_e32 v72, 5, v42
	s_ashr_i32 s0, s0, 1
	v_lshl_add_u64 v[32:33], v[60:61], 0, v[32:33]
	v_lshl_add_u64 v[36:37], v[60:61], 0, v[34:35]
	v_ashrrev_i32_e32 v71, 31, v70
	v_ashrrev_i32_e32 v73, 31, v72
	v_mov_b32_e32 v67, s0
	s_movk_i32 s0, 0xffe0
	global_load_dwordx4 v[32:35], v[32:33], off
	s_nop 0
	global_load_dwordx4 v[36:39], v[36:37], off
	v_lshlrev_b64 v[40:41], 9, v[70:71]
	v_lshlrev_b64 v[42:43], 9, v[72:73]
	v_ashrrev_i32_e32 v74, 5, v48
	v_ashrrev_i32_e32 v76, 5, v50
	v_bfi_b32 v167, s0, v67, v163
	v_lshl_add_u64 v[40:41], v[60:61], 0, v[40:41]
	v_lshl_add_u64 v[44:45], v[60:61], 0, v[42:43]
	v_ashrrev_i32_e32 v75, 31, v74
	v_ashrrev_i32_e32 v77, 31, v76
	v_ashrrev_i32_e32 v78, 5, v56
	v_ashrrev_i32_e32 v80, 5, v62
	v_add_u32_e32 v164, s18, v167
	v_mov_b64_e32 v[82:83], s[72:73]
	global_load_dwordx4 v[40:43], v[40:41], off
	s_nop 0
	global_load_dwordx4 v[44:47], v[44:45], off
	v_lshlrev_b64 v[48:49], 9, v[74:75]
	v_lshlrev_b64 v[50:51], 9, v[76:77]
	v_ashrrev_i32_e32 v79, 31, v78
	v_ashrrev_i32_e32 v81, 31, v80
	v_bfe_u32 v65, v163, 5, 1
	v_mad_i64_i32 v[82:83], s[0:1], v164, s15, v[82:83]
	v_lshl_add_u64 v[48:49], v[60:61], 0, v[48:49]
	v_lshl_add_u64 v[52:53], v[60:61], 0, v[50:51]
	v_lshlrev_b64 v[56:57], 9, v[78:79]
	v_lshlrev_b64 v[62:63], 9, v[80:81]
	v_lshl_add_u64 v[82:83], v[82:83], 0, s[74:75]
	v_lshlrev_b32_e32 v84, 4, v65
	v_mov_b32_e32 v85, v129
	global_load_dwordx4 v[48:51], v[48:49], off
	s_nop 0
	global_load_dwordx4 v[52:55], v[52:53], off
	v_lshl_add_u64 v[56:57], v[60:61], 0, v[56:57]
	v_lshl_add_u64 v[60:61], v[60:61], 0, v[62:63]
	v_lshl_add_u64 v[82:83], v[82:83], 0, v[84:85]
	global_load_dwordx4 v[56:59], v[56:57], off
	v_readlane_b32 s16, v254, 28
	global_load_dwordx4 v[60:63], v[60:61], off
	s_nop 0
	flat_load_dwordx4 v[130:133], v[82:83]
	flat_load_dwordx4 v[134:137], v[82:83] offset:32
	flat_load_dwordx4 v[138:141], v[82:83] offset:64
	flat_load_dwordx4 v[142:145], v[82:83] offset:96
	flat_load_dwordx4 v[146:149], v[82:83] offset:128
	flat_load_dwordx4 v[150:153], v[82:83] offset:160
	flat_load_dwordx4 v[154:157], v[82:83] offset:192
	flat_load_dwordx4 v[158:161], v[82:83] offset:224
	v_add_u32_e32 v82, 0, v128
	v_mad_u64_u32 v[86:87], s[0:1], v86, s86, v[82:83]
	s_waitcnt vmcnt(0) lgkmcnt(0)
; #define LAS __attribute__((address_space(3)))
; #define MFMA32(a, b, c) __builtin_amdgcn_mfma_f32_32x32x16_bf16((a), (b), (c), 0, 0, 0)
; template <bool CAUSAL>
; __device__ __forceinline__ void attn_tile(const LAS unsigned char* Ks, const LAS unsigned char* Vts, const bf16x8 (&qf)[8], int qi, int r32, int hi, f32x16 (&O)[4], float& m2, float& l) {
;     const float c = 0.08838834764831845f * 1.4426950408889634f;
;     float m = -1.0e30f, lsum = 0.f;
; #pragma unroll
;     for (int d = 0; d < 4; ++d)
; #pragma unroll
;         for (int r = 0; r < 16; ++r) O[d][r] = 0.f;
; #pragma unroll 1
;     for (int hf = 0; hf < 2; ++hf) {
;         f32x16 S[4];
; #pragma unroll
;         for (int s = 0; s < 4; ++s) {
;             f32x16 a;
; #pragma unroll
;             for (int r = 0; r < 16; ++r) a[r] = 0.f;
;             const LAS unsigned char* kp = Ks + (128 * hf + 32 * s + r32) * KS_STRIDE + 16 * hi;
; #pragma unroll
;             for (int d0 = 0; d0 < 8; ++d0) { const bf16x8 kf = *(const LAS bf16x8*)(kp + 32 * d0); a = MFMA32(kf, qf[d0], a); }
; __device__ __forceinline__ void stage_kv_store(LAS unsigned char* lds, const u32x4 (&kr)[8], const u32x4 (&vr)[8], int tid) {
; #pragma unroll
;     for (int i = 0; i < 8; ++i) { const int c = tid + 512 * i, row = c >> 4, ch = c & 15; *(LAS u32x4*)(lds + LDS_KS + row * KS_STRIDE + ch * 16) = kr[i]; }
; #pragma unroll
;     for (int i = 0; i < 8; ++i) { const int c = tid + 512 * i, row = c >> 5, ch = c & 31; *(LAS u32x4*)(lds + LDS_VT + row * VT_STRIDE + ch * 16) = vr[i]; }
; }
	ds_write_b128 v86, v[0:3]
	v_mad_u64_u32 v[0:1], s[0:1], v88, s86, v[82:83]
	ds_write_b128 v0, v[4:7]
	v_mad_u64_u32 v[0:1], s[0:1], v89, s86, v[82:83]
	ds_write_b128 v0, v[8:11]
	v_mad_u64_u32 v[0:1], s[0:1], v90, s86, v[82:83]
	ds_write_b128 v0, v[12:15]
	v_mad_u64_u32 v[0:1], s[0:1], v91, s86, v[82:83]
	ds_write_b128 v0, v[16:19]
	v_mad_u64_u32 v[0:1], s[0:1], v92, s86, v[82:83]
	ds_write_b128 v0, v[20:23]
	v_mad_u64_u32 v[0:1], s[0:1], v93, s86, v[82:83]
	s_movk_i32 s15, 0x210
	v_and_b32_e32 v166, 31, v163
	v_lshlrev_b32_e32 v162, 3, v65
	ds_write_b128 v0, v[24:27]
	v_mad_u64_u32 v[0:1], s[0:1], v94, s86, v[82:83]
	ds_write_b128 v0, v[28:31]
	v_add_u32_e32 v0, s16, v64
	v_mad_u64_u32 v[2:3], s[0:1], v66, s15, v[0:1]
	v_mov_b32_e32 v171, 0
	v_ashrrev_i32_e32 v165, 31, v164
	v_add_u32_e32 v128, 0, v84
	v_lshlrev_b32_e32 v168, 2, v65
	v_mov_b32_e32 v4, v171
	v_mov_b32_e32 v5, v171
	v_mov_b32_e32 v6, v171
	v_mov_b32_e32 v7, v171
	v_mov_b32_e32 v8, v171
	v_mov_b32_e32 v9, v171
	v_mov_b32_e32 v10, v171
	ds_write_b128 v2, v[32:35]
	v_mad_u64_u32 v[2:3], s[0:1], v68, s15, v[0:1]
	ds_write_b128 v2, v[36:39]
	v_mad_u64_u32 v[2:3], s[0:1], v70, s15, v[0:1]
	v_mov_b32_e32 v68, 0xf149f2ca
	v_mov_b32_e32 v11, v171
	v_mov_b32_e32 v12, v171
	v_mov_b32_e32 v13, v171
	v_mov_b32_e32 v14, v171
	v_mov_b32_e32 v15, v171
	v_mov_b32_e32 v16, 0
	v_mov_b32_e32 v17, v171
	ds_write_b128 v2, v[40:43]
	v_mad_u64_u32 v[2:3], s[0:1], v72, s15, v[0:1]
	ds_write_b128 v2, v[44:47]
	v_mad_u64_u32 v[2:3], s[0:1], v74, s15, v[0:1]
	v_mov_b32_e32 v18, v171
	v_mov_b32_e32 v19, v171
	v_mov_b32_e32 v20, v171
	v_mov_b32_e32 v21, v171
	v_mov_b32_e32 v22, v171
	v_mov_b32_e32 v23, v171
	v_mov_b32_e32 v24, v171
	v_mov_b32_e32 v25, v171
	v_mov_b32_e32 v26, v171
	ds_write_b128 v2, v[48:51]
	v_mad_u64_u32 v[2:3], s[0:1], v76, s15, v[0:1]
	ds_write_b128 v2, v[52:55]
	v_mad_u64_u32 v[2:3], s[0:1], v78, s15, v[0:1]
	v_mad_u64_u32 v[0:1], s[0:1], v80, s15, v[0:1]
	v_and_b32_e32 v1, 64, v237
	ds_write_b128 v2, v[56:59]
	ds_write_b128 v0, v[60:63]
	v_xor_b32_e32 v0, 32, v237
	v_add_u32_e32 v1, 64, v1
	v_cmp_lt_i32_e32 vcc, v0, v1
	s_mov_b32 s15, 0
	s_mov_b64 s[0:1], -1
	v_cndmask_b32_e32 v0, v237, v0, vcc
	v_lshlrev_b32_e32 v169, 2, v0
	v_mul_u32_u24_e32 v0, 0x210, v166
	v_add3_u32 v170, s16, v162, v0
	v_mov_b32_e32 v0, 0
	v_mov_b32_e32 v1, v171
	v_mov_b32_e32 v2, v171
	v_mov_b32_e32 v3, v171
	v_mov_b32_e32 v27, v171
	v_mov_b32_e32 v28, v171
	v_mov_b32_e32 v29, v171
	v_mov_b32_e32 v30, v171
	v_mov_b32_e32 v31, v171
	v_mov_b32_e32 v32, 0
	v_mov_b32_e32 v33, v171
	v_mov_b32_e32 v34, v171
	v_mov_b32_e32 v35, v171
	v_mov_b32_e32 v36, v171
	v_mov_b32_e32 v37, v171
	v_mov_b32_e32 v38, v171
	v_mov_b32_e32 v39, v171
	v_mov_b32_e32 v40, v171
	v_mov_b32_e32 v41, v171
	v_mov_b32_e32 v42, v171
	v_mov_b32_e32 v43, v171
	v_mov_b32_e32 v44, v171
	v_mov_b32_e32 v45, v171
	v_mov_b32_e32 v46, v171
	v_mov_b32_e32 v47, v171
	v_mov_b32_e32 v48, 0
	v_mov_b32_e32 v49, v171
	v_mov_b32_e32 v50, v171
	v_mov_b32_e32 v51, v171
	v_mov_b32_e32 v52, v171
	v_mov_b32_e32 v53, v171
	v_mov_b32_e32 v54, v171
	v_mov_b32_e32 v55, v171
	v_mov_b32_e32 v56, v171
	v_mov_b32_e32 v57, v171
	v_mov_b32_e32 v58, v171
	v_mov_b32_e32 v59, v171
	v_mov_b32_e32 v60, v171
	v_mov_b32_e32 v61, v171
	v_mov_b32_e32 v62, v171
	v_mov_b32_e32 v63, v171
	s_waitcnt lgkmcnt(0)
	s_barrier
	v_readfirstlane_b32 s99, v232
	s_cmpk_lt_u32 s99, 0x100
	s_cbranch_scc0 .Lown_full
	s_mov_b64 s[0:1], 0
.Lown_full:
.LBB0_23:
	s_lshl_b32 s16, s15, 7
	v_or_b32_e32 v64, s16, v166
	v_mad_u32_u24 v176, v64, s86, v128
	ds_read_b128 v[64:67], v176
	v_mov_b32_e32 v182, v68
	s_waitcnt lgkmcnt(0)
	v_mfma_f32_32x32x16_bf16 v[112:127], v[64:67], v[130:133], 0
	ds_read_b128 v[64:67], v176 offset:32
	s_waitcnt lgkmcnt(0)
	v_mfma_f32_32x32x16_bf16 v[112:127], v[64:67], v[134:137], v[112:127]
	ds_read_b128 v[64:67], v176 offset:64
	s_waitcnt lgkmcnt(0)
	v_mfma_f32_32x32x16_bf16 v[112:127], v[64:67], v[138:141], v[112:127]
	ds_read_b128 v[64:67], v176 offset:96
	s_waitcnt lgkmcnt(0)
	v_mfma_f32_32x32x16_bf16 v[112:127], v[64:67], v[142:145], v[112:127]
	ds_read_b128 v[64:67], v176 offset:128
	s_waitcnt lgkmcnt(0)
	v_mfma_f32_32x32x16_bf16 v[112:127], v[64:67], v[146:149], v[112:127]
	ds_read_b128 v[64:67], v176 offset:160
	s_waitcnt lgkmcnt(0)
	v_mfma_f32_32x32x16_bf16 v[112:127], v[64:67], v[150:153], v[112:127]
	ds_read_b128 v[64:67], v176 offset:192
	s_waitcnt lgkmcnt(0)
	v_mfma_f32_32x32x16_bf16 v[112:127], v[64:67], v[154:157], v[112:127]
	ds_read_b128 v[64:67], v176 offset:224
	s_waitcnt lgkmcnt(0)
	v_mfma_f32_32x32x16_bf16 v[112:127], v[64:67], v[158:161], v[112:127]
	ds_read_b128 v[64:67], v176 offset:8704
	s_waitcnt lgkmcnt(0)
	v_mfma_f32_32x32x16_bf16 v[96:111], v[64:67], v[130:133], 0
	ds_read_b128 v[64:67], v176 offset:8736
	s_waitcnt lgkmcnt(0)
	v_mfma_f32_32x32x16_bf16 v[96:111], v[64:67], v[134:137], v[96:111]
	ds_read_b128 v[64:67], v176 offset:8768
	s_waitcnt lgkmcnt(0)
	v_mfma_f32_32x32x16_bf16 v[96:111], v[64:67], v[138:141], v[96:111]
	ds_read_b128 v[64:67], v176 offset:8800
	s_waitcnt lgkmcnt(0)
	v_mfma_f32_32x32x16_bf16 v[96:111], v[64:67], v[142:145], v[96:111]
	ds_read_b128 v[64:67], v176 offset:8832
	s_waitcnt lgkmcnt(0)
	v_mfma_f32_32x32x16_bf16 v[96:111], v[64:67], v[146:149], v[96:111]
	ds_read_b128 v[64:67], v176 offset:8864
	s_waitcnt lgkmcnt(0)
	v_mfma_f32_32x32x16_bf16 v[96:111], v[64:67], v[150:153], v[96:111]
	ds_read_b128 v[64:67], v176 offset:8896
	s_waitcnt lgkmcnt(0)
	v_mfma_f32_32x32x16_bf16 v[96:111], v[64:67], v[154:157], v[96:111]
	ds_read_b128 v[64:67], v176 offset:8928
	s_waitcnt lgkmcnt(0)
; #define LAS __attribute__((address_space(3)))
; __device__ __forceinline__ int crow(int r, int hi) { return (r & 3) + 8 * (r >> 2) + 4 * hi; }
; #define MFMA32(a, b, c) __builtin_amdgcn_mfma_f32_32x32x16_bf16((a), (b), (c), 0, 0, 0)
; template <bool CAUSAL>
; __device__ __forceinline__ void attn_tile(const LAS unsigned char* Ks, const LAS unsigned char* Vts, const bf16x8 (&qf)[8], int qi, int r32, int hi, f32x16 (&O)[4], float& m2, float& l) {
;     ...
;             for (int d0 = 0; d0 < 8; ++d0) { const bf16x8 kf = *(const LAS bf16x8*)(kp + 32 * d0); a = MFMA32(kf, qf[d0], a); }
;             S[s] = a;
;             __builtin_amdgcn_sched_barrier(0);
;         }
;         float mx = -1.0e30f;
; #pragma unroll
;         for (int s = 0; s < 4; ++s)
; #pragma unroll
;             for (int r = 0; r < 16; ++r) { float v = S[s][r]; if (CAUSAL) { if (128 * hf + 32 * s + crow(r, hi) > qi) v = -INFINITY; S[s][r] = v; } mx = fmaxf(mx, v); }
	v_mfma_f32_32x32x16_bf16 v[96:111], v[64:67], v[158:161], v[96:111]
	ds_read_b128 v[64:67], v176 offset:17408
	s_waitcnt lgkmcnt(0)
	v_mfma_f32_32x32x16_bf16 v[80:95], v[64:67], v[130:133], 0
	ds_read_b128 v[64:67], v176 offset:17440
	s_waitcnt lgkmcnt(0)
	v_mfma_f32_32x32x16_bf16 v[80:95], v[64:67], v[134:137], v[80:95]
	ds_read_b128 v[64:67], v176 offset:17472
	s_waitcnt lgkmcnt(0)
	v_mfma_f32_32x32x16_bf16 v[80:95], v[64:67], v[138:141], v[80:95]
	ds_read_b128 v[64:67], v176 offset:17504
	s_waitcnt lgkmcnt(0)
	v_mfma_f32_32x32x16_bf16 v[80:95], v[64:67], v[142:145], v[80:95]
	ds_read_b128 v[64:67], v176 offset:17536
	s_waitcnt lgkmcnt(0)
	v_mfma_f32_32x32x16_bf16 v[80:95], v[64:67], v[146:149], v[80:95]
	ds_read_b128 v[64:67], v176 offset:17568
	s_waitcnt lgkmcnt(0)
	v_mfma_f32_32x32x16_bf16 v[80:95], v[64:67], v[150:153], v[80:95]
	ds_read_b128 v[64:67], v176 offset:17600
	s_waitcnt lgkmcnt(0)
	v_mfma_f32_32x32x16_bf16 v[80:95], v[64:67], v[154:157], v[80:95]
	ds_read_b128 v[64:67], v176 offset:17632
	s_waitcnt lgkmcnt(0)
	v_mfma_f32_32x32x16_bf16 v[80:95], v[64:67], v[158:161], v[80:95]
	ds_read_b128 v[64:67], v176 offset:26112
	ds_read_b128 v[172:175], v176 offset:26144
	s_waitcnt lgkmcnt(1)
	v_mfma_f32_32x32x16_bf16 v[64:79], v[64:67], v[130:133], 0
	s_waitcnt lgkmcnt(0)
	v_mfma_f32_32x32x16_bf16 v[64:79], v[172:175], v[134:137], v[64:79]
	ds_read_b128 v[172:175], v176 offset:26176
	s_waitcnt lgkmcnt(0)
	v_mfma_f32_32x32x16_bf16 v[64:79], v[172:175], v[138:141], v[64:79]
	ds_read_b128 v[172:175], v176 offset:26208
	s_waitcnt lgkmcnt(0)
	v_mfma_f32_32x32x16_bf16 v[64:79], v[172:175], v[142:145], v[64:79]
	ds_read_b128 v[172:175], v176 offset:26240
	s_waitcnt lgkmcnt(0)
	v_mfma_f32_32x32x16_bf16 v[64:79], v[172:175], v[146:149], v[64:79]
	ds_read_b128 v[172:175], v176 offset:26272
	s_waitcnt lgkmcnt(0)
	v_mfma_f32_32x32x16_bf16 v[64:79], v[172:175], v[150:153], v[64:79]
	ds_read_b128 v[172:175], v176 offset:26304
	s_waitcnt lgkmcnt(0)
	v_mfma_f32_32x32x16_bf16 v[64:79], v[172:175], v[154:157], v[64:79]
	ds_read_b128 v[172:175], v176 offset:26336
	s_waitcnt lgkmcnt(0)
	v_mfma_f32_32x32x16_bf16 v[64:79], v[172:175], v[158:161], v[64:79]
	v_or_b32_e32 v174, s16, v168
	v_cmp_le_i32_e32 vcc, v174, v167
	s_nop 1
	v_cndmask_b32_e32 v176, v238, v112, vcc
	v_cmp_lt_i32_e32 vcc, v174, v167
	s_nop 1
	v_cndmask_b32_e32 v183, v238, v113, vcc
	v_or_b32_e32 v113, 2, v174
	v_cmp_le_i32_e32 vcc, v113, v167
	v_or_b32_e32 v113, 3, v174
	v_max3_f32 v112, v176, s69, v183
	v_cndmask_b32_e32 v114, v238, v114, vcc
	v_cmp_le_i32_e32 vcc, v113, v167
	v_or_b32_e32 v113, 8, v174
	s_nop 0
	v_cndmask_b32_e32 v184, v238, v115, vcc
	v_cmp_le_i32_e32 vcc, v113, v167
	v_or_b32_e32 v113, 9, v174
	v_max3_f32 v112, v112, v114, v184
	v_cndmask_b32_e32 v116, v238, v116, vcc
	v_cmp_le_i32_e32 vcc, v113, v167
	v_or_b32_e32 v113, 10, v174
	s_nop 0
	v_cndmask_b32_e32 v185, v238, v117, vcc
	v_cmp_le_i32_e32 vcc, v113, v167
	v_or_b32_e32 v113, 11, v174
	v_max3_f32 v112, v112, v116, v185
	v_cndmask_b32_e32 v186, v238, v118, vcc
	v_cmp_le_i32_e32 vcc, v113, v167
	v_or_b32_e32 v113, 16, v174
	s_nop 0
	v_cndmask_b32_e32 v187, v238, v119, vcc
	v_cmp_le_i32_e32 vcc, v113, v167
	v_or_b32_e32 v113, 17, v174
	v_max3_f32 v112, v112, v186, v187
	v_cndmask_b32_e32 v120, v238, v120, vcc
	v_cmp_le_i32_e32 vcc, v113, v167
	v_or_b32_e32 v113, 18, v174
	s_nop 0
	v_cndmask_b32_e32 v188, v238, v121, vcc
	v_cmp_le_i32_e32 vcc, v113, v167
	v_or_b32_e32 v113, 19, v174
	v_max3_f32 v112, v112, v120, v188
	v_cndmask_b32_e32 v189, v238, v122, vcc
	v_cmp_le_i32_e32 vcc, v113, v167
	v_or_b32_e32 v113, 24, v174
	s_nop 0
	v_cndmask_b32_e32 v123, v238, v123, vcc
	v_cmp_le_i32_e32 vcc, v113, v167
	v_or_b32_e32 v113, 25, v174
	v_max3_f32 v112, v112, v189, v123
	v_cndmask_b32_e32 v190, v238, v124, vcc
	v_cmp_le_i32_e32 vcc, v113, v167
	v_or_b32_e32 v113, 26, v174
	s_nop 0
	v_cndmask_b32_e32 v125, v238, v125, vcc
	v_cmp_le_i32_e32 vcc, v113, v167
	v_or_b32_e32 v113, 27, v174
	v_max3_f32 v112, v112, v190, v125
	v_cndmask_b32_e32 v191, v238, v126, vcc
	v_cmp_le_i32_e32 vcc, v113, v167
	v_or_b32_e32 v113, 32, v174
	s_nop 0
	v_cndmask_b32_e32 v192, v238, v127, vcc
	v_cmp_le_i32_e32 vcc, v113, v167
	v_max3_f32 v112, v112, v191, v192
	s_nop 0
	v_cndmask_b32_e32 v193, v238, v96, vcc
	v_or_b32_e32 v96, 33, v174
	v_cmp_le_i32_e32 vcc, v96, v167
	s_nop 1
	v_cndmask_b32_e32 v97, v238, v97, vcc
	v_max3_f32 v96, v112, v193, v97
	v_or_b32_e32 v112, 34, v174
	v_cmp_le_i32_e32 vcc, v112, v167
	s_nop 1
	v_cndmask_b32_e32 v194, v238, v98, vcc
	v_or_b32_e32 v98, 35, v174
	v_cmp_le_i32_e32 vcc, v98, v167
	v_or_b32_e32 v98, 40, v174
	s_nop 0
	v_cndmask_b32_e32 v195, v238, v99, vcc
	v_cmp_le_i32_e32 vcc, v98, v167
	v_or_b32_e32 v98, 41, v174
	v_or_b32_e32 v99, 51, v174
	v_cndmask_b32_e32 v196, v238, v100, vcc
	v_cmp_le_i32_e32 vcc, v98, v167
	v_or_b32_e32 v98, 42, v174
	v_max3_f32 v96, v96, v194, v195
	v_cndmask_b32_e32 v197, v238, v101, vcc
	v_cmp_le_i32_e32 vcc, v98, v167
	v_or_b32_e32 v98, 43, v174
	v_max3_f32 v96, v96, v196, v197
	v_cndmask_b32_e32 v172, v238, v102, vcc
	v_cmp_le_i32_e32 vcc, v98, v167
	v_or_b32_e32 v98, 48, v174
	s_nop 0
	v_cndmask_b32_e32 v175, v238, v103, vcc
	v_cmp_le_i32_e32 vcc, v98, v167
	v_or_b32_e32 v98, 49, v174
	v_max3_f32 v96, v96, v172, v175
	v_cndmask_b32_e32 v181, v238, v104, vcc
	v_cmp_le_i32_e32 vcc, v98, v167
	v_or_b32_e32 v98, 50, v174
	s_nop 0
	v_cndmask_b32_e32 v180, v238, v105, vcc
	v_cmp_le_i32_e32 vcc, v98, v167
	v_max3_f32 v96, v96, v181, v180
	s_nop 0
	v_cndmask_b32_e32 v98, v238, v106, vcc
	v_cmp_le_i32_e32 vcc, v99, v167
	v_or_b32_e32 v99, 56, v174
	s_nop 0
	v_cndmask_b32_e32 v179, v238, v107, vcc
; __device__ __forceinline__ int crow(int r, int hi) { return (r & 3) + 8 * (r >> 2) + 4 * hi; }
; template <bool CAUSAL>
; __device__ __forceinline__ void attn_tile(const LAS unsigned char* Ks, const LAS unsigned char* Vts, const bf16x8 (&qf)[8], int qi, int r32, int hi, f32x16 (&O)[4], float& m2, float& l) {
;     ...
;         for (int s = 0; s < 4; ++s)
; #pragma unroll
;             for (int r = 0; r < 16; ++r) { float v = S[s][r]; if (CAUSAL) { if (128 * hf + 32 * s + crow(r, hi) > qi) v = -INFINITY; S[s][r] = v; } mx = fmaxf(mx, v); }
;         mx = fmaxf(mx, __shfl_xor(mx, 32));
	v_cmp_le_i32_e32 vcc, v99, v167
	v_or_b32_e32 v99, 57, v174
	v_max3_f32 v96, v96, v98, v179
	v_cndmask_b32_e32 v117, v238, v108, vcc
	v_cmp_le_i32_e32 vcc, v99, v167
	v_or_b32_e32 v99, 58, v174
	s_nop 0
	v_cndmask_b32_e32 v121, v238, v109, vcc
	v_cmp_le_i32_e32 vcc, v99, v167
	v_or_b32_e32 v99, 59, v174
	v_max3_f32 v96, v96, v117, v121
	v_cndmask_b32_e32 v126, v238, v110, vcc
	v_cmp_le_i32_e32 vcc, v99, v167
	v_or_b32_e32 v99, 64, v174
	s_nop 0
	v_cndmask_b32_e32 v173, v238, v111, vcc
	v_cmp_le_i32_e32 vcc, v99, v167
	v_max3_f32 v96, v96, v126, v173
	s_nop 0
	v_cndmask_b32_e32 v178, v238, v80, vcc
	v_or_b32_e32 v80, 0x41, v174
	v_cmp_le_i32_e32 vcc, v80, v167
	s_nop 1
	v_cndmask_b32_e32 v177, v238, v81, vcc
	v_or_b32_e32 v81, 0x42, v174
	v_cmp_le_i32_e32 vcc, v81, v167
	v_or_b32_e32 v81, 0x43, v174
	v_max3_f32 v80, v96, v178, v177
	v_cndmask_b32_e32 v127, v238, v82, vcc
	v_cmp_le_i32_e32 vcc, v81, v167
	v_or_b32_e32 v81, 0x48, v174
	s_nop 0
	v_cndmask_b32_e32 v101, v238, v83, vcc
	v_cmp_le_i32_e32 vcc, v81, v167
	v_or_b32_e32 v81, 0x49, v174
	v_max3_f32 v80, v80, v127, v101
	v_cndmask_b32_e32 v115, v238, v84, vcc
	v_cmp_le_i32_e32 vcc, v81, v167
	v_or_b32_e32 v81, 0x4a, v174
	s_nop 0
	v_cndmask_b32_e32 v118, v238, v85, vcc
	v_cmp_le_i32_e32 vcc, v81, v167
	v_or_b32_e32 v81, 0x4b, v174
	v_max3_f32 v80, v80, v115, v118
	v_cndmask_b32_e32 v122, v238, v86, vcc
	v_cmp_le_i32_e32 vcc, v81, v167
	v_or_b32_e32 v81, 0x50, v174
	s_nop 0
	v_cndmask_b32_e32 v124, v238, v87, vcc
	v_cmp_le_i32_e32 vcc, v81, v167
	v_or_b32_e32 v81, 0x51, v174
	v_max3_f32 v80, v80, v122, v124
	v_cndmask_b32_e32 v86, v238, v88, vcc
	v_cmp_le_i32_e32 vcc, v81, v167
	v_or_b32_e32 v81, 0x52, v174
	s_nop 0
	v_cndmask_b32_e32 v88, v238, v89, vcc
	v_cmp_le_i32_e32 vcc, v81, v167
	v_or_b32_e32 v81, 0x53, v174
	v_max3_f32 v80, v80, v86, v88
	v_cndmask_b32_e32 v119, v238, v90, vcc
	v_cmp_le_i32_e32 vcc, v81, v167
	v_or_b32_e32 v81, 0x58, v174
	s_nop 0
	v_cndmask_b32_e32 v96, v238, v91, vcc
	v_cmp_le_i32_e32 vcc, v81, v167
	v_or_b32_e32 v81, 0x59, v174
	v_max3_f32 v80, v80, v119, v96
	v_cndmask_b32_e32 v112, v238, v92, vcc
	v_cmp_le_i32_e32 vcc, v81, v167
	v_or_b32_e32 v81, 0x5a, v174
	s_nop 0
	v_cndmask_b32_e32 v106, v238, v93, vcc
	v_cmp_le_i32_e32 vcc, v81, v167
	v_or_b32_e32 v81, 0x5b, v174
	v_max3_f32 v80, v80, v112, v106
	v_cndmask_b32_e32 v85, v238, v94, vcc
	v_cmp_le_i32_e32 vcc, v81, v167
	v_or_b32_e32 v81, 0x60, v174
	s_nop 0
	v_cndmask_b32_e32 v84, v238, v95, vcc
	v_cmp_le_i32_e32 vcc, v81, v167
	v_or_b32_e32 v81, 0x61, v174
	v_max3_f32 v80, v80, v85, v84
	v_cndmask_b32_e32 v64, v238, v64, vcc
	v_cmp_le_i32_e32 vcc, v81, v167
	v_or_b32_e32 v81, 0x62, v174
	s_nop 0
	v_cndmask_b32_e32 v65, v238, v65, vcc
	v_cmp_le_i32_e32 vcc, v81, v167
	v_or_b32_e32 v81, 0x63, v174
	v_max3_f32 v80, v80, v64, v65
	v_cndmask_b32_e32 v66, v238, v66, vcc
	v_cmp_le_i32_e32 vcc, v81, v167
	s_nop 1
	v_cndmask_b32_e32 v67, v238, v67, vcc
	v_max3_f32 v82, v80, v66, v67
	v_or_b32_e32 v80, 0x68, v174
	v_cmp_le_i32_e32 vcc, v80, v167
	s_nop 1
	v_cndmask_b32_e32 v80, v238, v68, vcc
	v_or_b32_e32 v68, 0x69, v174
	v_cmp_le_i32_e32 vcc, v68, v167
	s_nop 1
	v_cndmask_b32_e32 v81, v238, v69, vcc
	v_or_b32_e32 v69, 0x6a, v174
	v_cmp_le_i32_e32 vcc, v69, v167
	v_or_b32_e32 v69, 0x6b, v174
	v_max3_f32 v68, v82, v80, v81
	v_cndmask_b32_e32 v82, v238, v70, vcc
	v_cmp_le_i32_e32 vcc, v69, v167
	v_or_b32_e32 v69, 0x70, v174
	s_nop 0
	v_cndmask_b32_e32 v83, v238, v71, vcc
	v_cmp_le_i32_e32 vcc, v69, v167
	v_or_b32_e32 v69, 0x71, v174
	v_max3_f32 v68, v68, v82, v83
	v_cndmask_b32_e32 v99, v238, v72, vcc
	v_cmp_le_i32_e32 vcc, v69, v167
	v_or_b32_e32 v69, 0x72, v174
	s_nop 0
	v_cndmask_b32_e32 v100, v238, v73, vcc
	v_cmp_le_i32_e32 vcc, v69, v167
	v_or_b32_e32 v69, 0x73, v174
	v_max3_f32 v68, v68, v99, v100
	v_cndmask_b32_e32 v102, v238, v74, vcc
	v_cmp_le_i32_e32 vcc, v69, v167
	v_or_b32_e32 v69, 0x78, v174
	s_nop 0
	v_cndmask_b32_e32 v104, v238, v75, vcc
	v_cmp_le_i32_e32 vcc, v69, v167
	v_or_b32_e32 v69, 0x79, v174
	v_max3_f32 v68, v68, v102, v104
	v_cndmask_b32_e32 v107, v238, v76, vcc
	v_cmp_le_i32_e32 vcc, v69, v167
	v_or_b32_e32 v69, 0x7a, v174
	s_nop 0
	v_cndmask_b32_e32 v109, v238, v77, vcc
	v_cmp_le_i32_e32 vcc, v69, v167
	v_or_b32_e32 v69, 0x7b, v174
	v_max3_f32 v68, v68, v107, v109
	v_cndmask_b32_e32 v110, v238, v78, vcc
	v_cmp_le_i32_e32 vcc, v69, v167
	s_nop 1
	v_cndmask_b32_e32 v113, v238, v79, vcc
	v_max3_f32 v68, v68, v110, v113
	ds_bpermute_b32 v69, v169, v68
	s_waitcnt lgkmcnt(0)
; template <bool CAUSAL>
; __device__ __forceinline__ void attn_tile(const LAS unsigned char* Ks, const LAS unsigned char* Vts, const bf16x8 (&qf)[8], int qi, int r32, int hi, f32x16 (&O)[4], float& m2, float& l) {
;     ...
;         mx = fmaxf(mx, __shfl_xor(mx, 32));
;         const float mn = fmaxf(m, mx * c), alpha = __builtin_amdgcn_exp2f(m - mn);
;         m = mn; lsum *= alpha;
; #pragma unroll
;         for (int d = 0; d < 4; ++d)
; #pragma unroll
;             for (int r = 0; r < 16; ++r) O[d][r] *= alpha;
; #pragma unroll
;         for (int s = 0; s < 4; ++s)
; #pragma unroll
;             for (int r = 0; r < 16; ++r) { const float p = __builtin_amdgcn_exp2f(S[s][r] * c - mn); S[s][r] = p; lsum += p; }
	v_max_f32_e32 v69, v69, v69
	v_max_f32_e32 v68, v68, v69
	v_mul_f32_e32 v68, 0x3e0293ee, v68
	v_max_f32_e32 v69, v182, v182
	v_max_f32_e32 v68, v69, v68
	v_sub_f32_e32 v69, v182, v68
	v_exp_f32_e32 v70, v69
	v_fma_f32 v69, v176, s87, -v68
	v_exp_f32_e32 v182, v69
	v_fma_f32 v64, v64, s87, -v68
	v_pk_mul_f32 v[62:63], v[62:63], v[70:71] op_sel_hi:[1,0]
	v_pk_mul_f32 v[60:61], v[60:61], v[70:71] op_sel_hi:[1,0]
	v_pk_mul_f32 v[58:59], v[58:59], v[70:71] op_sel_hi:[1,0]
	v_pk_mul_f32 v[56:57], v[56:57], v[70:71] op_sel_hi:[1,0]
	v_pk_mul_f32 v[54:55], v[54:55], v[70:71] op_sel_hi:[1,0]
	v_pk_mul_f32 v[52:53], v[52:53], v[70:71] op_sel_hi:[1,0]
	v_pk_mul_f32 v[50:51], v[50:51], v[70:71] op_sel_hi:[1,0]
	v_pk_mul_f32 v[48:49], v[48:49], v[70:71] op_sel_hi:[1,0]
	v_pk_mul_f32 v[46:47], v[46:47], v[70:71] op_sel_hi:[1,0]
	v_pk_mul_f32 v[44:45], v[44:45], v[70:71] op_sel_hi:[1,0]
	v_pk_mul_f32 v[42:43], v[42:43], v[70:71] op_sel_hi:[1,0]
	v_pk_mul_f32 v[40:41], v[40:41], v[70:71] op_sel_hi:[1,0]
	v_pk_mul_f32 v[38:39], v[38:39], v[70:71] op_sel_hi:[1,0]
	v_pk_mul_f32 v[36:37], v[36:37], v[70:71] op_sel_hi:[1,0]
	v_pk_mul_f32 v[34:35], v[34:35], v[70:71] op_sel_hi:[1,0]
	v_pk_mul_f32 v[32:33], v[32:33], v[70:71] op_sel_hi:[1,0]
	v_pk_mul_f32 v[30:31], v[30:31], v[70:71] op_sel_hi:[1,0]
	v_pk_mul_f32 v[28:29], v[28:29], v[70:71] op_sel_hi:[1,0]
	v_pk_mul_f32 v[26:27], v[26:27], v[70:71] op_sel_hi:[1,0]
	v_pk_mul_f32 v[24:25], v[24:25], v[70:71] op_sel_hi:[1,0]
	v_pk_mul_f32 v[22:23], v[22:23], v[70:71] op_sel_hi:[1,0]
	v_pk_mul_f32 v[20:21], v[20:21], v[70:71] op_sel_hi:[1,0]
	v_pk_mul_f32 v[18:19], v[18:19], v[70:71] op_sel_hi:[1,0]
	v_pk_mul_f32 v[16:17], v[16:17], v[70:71] op_sel_hi:[1,0]
	v_pk_mul_f32 v[14:15], v[14:15], v[70:71] op_sel_hi:[1,0]
	v_pk_mul_f32 v[12:13], v[12:13], v[70:71] op_sel_hi:[1,0]
	v_pk_mul_f32 v[10:11], v[10:11], v[70:71] op_sel_hi:[1,0]
	v_pk_mul_f32 v[8:9], v[8:9], v[70:71] op_sel_hi:[1,0]
	v_pk_mul_f32 v[6:7], v[6:7], v[70:71] op_sel_hi:[1,0]
	v_pk_mul_f32 v[4:5], v[4:5], v[70:71] op_sel_hi:[1,0]
	v_pk_mul_f32 v[2:3], v[2:3], v[70:71] op_sel_hi:[1,0]
	v_pk_mul_f32 v[0:1], v[0:1], v[70:71] op_sel_hi:[1,0]
	v_fma_f32 v69, v171, v70, v182
	v_fma_f32 v70, v183, s87, -v68
	v_exp_f32_e32 v183, v70
	v_fma_f32 v70, v114, s87, -v68
	v_exp_f32_e32 v198, v70
	v_fma_f32 v70, v184, s87, -v68
	v_exp_f32_e32 v184, v70
	v_fma_f32 v70, v116, s87, -v68
	v_exp_f32_e32 v199, v70
	v_fma_f32 v70, v185, s87, -v68
	v_add_f32_e32 v69, v183, v69
	v_exp_f32_e32 v185, v70
	v_fma_f32 v70, v186, s87, -v68
	v_add_f32_e32 v69, v198, v69
	v_exp_f32_e32 v186, v70
	v_fma_f32 v70, v187, s87, -v68
	v_add_f32_e32 v69, v184, v69
	v_exp_f32_e32 v187, v70
	v_fma_f32 v70, v120, s87, -v68
	v_add_f32_e32 v69, v199, v69
	v_exp_f32_e32 v95, v70
	v_fma_f32 v70, v188, s87, -v68
	v_add_f32_e32 v69, v185, v69
	v_exp_f32_e32 v103, v70
	v_fma_f32 v70, v189, s87, -v68
	v_add_f32_e32 v69, v186, v69
	v_exp_f32_e32 v111, v70
	v_fma_f32 v70, v123, s87, -v68
	v_add_f32_e32 v69, v187, v69
	v_exp_f32_e32 v116, v70
	v_fma_f32 v70, v190, s87, -v68
	v_add_f32_e32 v69, v95, v69
	v_exp_f32_e32 v123, v70
	v_fma_f32 v70, v125, s87, -v68
	v_add_f32_e32 v69, v103, v69
	v_exp_f32_e32 v171, v70
	v_fma_f32 v70, v191, s87, -v68
	v_add_f32_e32 v69, v111, v69
	v_exp_f32_e32 v174, v70
	v_fma_f32 v70, v192, s87, -v68
	v_add_f32_e32 v69, v116, v69
	v_exp_f32_e32 v176, v70
	v_fma_f32 v70, v193, s87, -v68
	v_add_f32_e32 v69, v123, v69
	v_exp_f32_e32 v92, v70
	v_fma_f32 v70, v97, s87, -v68
	v_add_f32_e32 v69, v171, v69
	v_exp_f32_e32 v97, v70
	v_fma_f32 v70, v194, s87, -v68
	v_add_f32_e32 v69, v174, v69
	v_exp_f32_e32 v105, v70
	v_fma_f32 v70, v195, s87, -v68
	v_add_f32_e32 v69, v176, v69
	v_exp_f32_e32 v114, v70
	v_fma_f32 v70, v196, s87, -v68
	v_add_f32_e32 v69, v92, v69
	v_exp_f32_e32 v120, v70
	v_fma_f32 v70, v197, s87, -v68
	v_add_f32_e32 v69, v97, v69
	v_exp_f32_e32 v125, v70
	v_fma_f32 v70, v172, s87, -v68
	v_add_f32_e32 v69, v105, v69
	v_exp_f32_e32 v172, v70
	v_fma_f32 v70, v175, s87, -v68
	v_add_f32_e32 v69, v114, v69
	v_exp_f32_e32 v175, v70
	v_fma_f32 v70, v181, s87, -v68
	v_add_f32_e32 v69, v120, v69
	v_exp_f32_e32 v89, v70
	v_fma_f32 v70, v180, s87, -v68
	v_add_f32_e32 v69, v125, v69
	v_exp_f32_e32 v93, v70
	v_fma_f32 v70, v98, s87, -v68
	v_add_f32_e32 v69, v172, v69
	v_exp_f32_e32 v98, v70
	v_fma_f32 v70, v179, s87, -v68
	v_add_f32_e32 v69, v175, v69
	v_exp_f32_e32 v108, v70
	v_fma_f32 v70, v117, s87, -v68
	v_add_f32_e32 v69, v89, v69
	v_exp_f32_e32 v117, v70
	v_fma_f32 v70, v121, s87, -v68
	v_add_f32_e32 v69, v93, v69
	v_exp_f32_e32 v121, v70
	v_fma_f32 v70, v126, s87, -v68
	v_add_f32_e32 v69, v98, v69
	v_exp_f32_e32 v126, v70
	v_fma_f32 v70, v173, s87, -v68
	v_add_f32_e32 v69, v108, v69
	v_exp_f32_e32 v173, v70
	v_fma_f32 v70, v178, s87, -v68
	v_add_f32_e32 v69, v117, v69
	v_exp_f32_e32 v87, v70
	v_fma_f32 v70, v177, s87, -v68
	v_add_f32_e32 v69, v121, v69
	v_exp_f32_e32 v90, v70
	v_fma_f32 v70, v127, s87, -v68
	v_add_f32_e32 v69, v126, v69
	v_exp_f32_e32 v94, v70
	v_fma_f32 v70, v101, s87, -v68
	v_add_f32_e32 v69, v173, v69
	v_exp_f32_e32 v101, v70
	v_fma_f32 v70, v115, s87, -v68
	v_add_f32_e32 v69, v87, v69
	v_exp_f32_e32 v115, v70
	v_fma_f32 v70, v118, s87, -v68
	v_add_f32_e32 v69, v90, v69
	v_exp_f32_e32 v118, v70
	v_fma_f32 v70, v122, s87, -v68
	v_add_f32_e32 v69, v94, v69
	v_exp_f32_e32 v122, v70
	v_fma_f32 v70, v124, s87, -v68
	v_add_f32_e32 v69, v101, v69
	v_exp_f32_e32 v127, v70
	v_fma_f32 v70, v86, s87, -v68
	v_add_f32_e32 v69, v115, v69
	v_exp_f32_e32 v86, v70
	v_fma_f32 v70, v88, s87, -v68
	v_add_f32_e32 v69, v118, v69
	v_exp_f32_e32 v88, v70
	v_fma_f32 v70, v119, s87, -v68
; #define LAS __attribute__((address_space(3)))
; __device__ __forceinline__ unsigned cvtpk(float lo, float hi) { f32x2 v = {lo, hi}; bf16x2_t b = __builtin_convertvector(v, bf16x2_t); return __builtin_bit_cast(unsigned, b); }
; #define MFMA32(a, b, c) __builtin_amdgcn_mfma_f32_32x32x16_bf16((a), (b), (c), 0, 0, 0)
; template <bool CAUSAL>
; __device__ __forceinline__ void attn_tile(const LAS unsigned char* Ks, const LAS unsigned char* Vts, const bf16x8 (&qf)[8], int qi, int r32, int hi, f32x16 (&O)[4], float& m2, float& l) {
;     ...
;             for (int r = 0; r < 16; ++r) { const float p = __builtin_amdgcn_exp2f(S[s][r] * c - mn); S[s][r] = p; lsum += p; }
; #pragma unroll
;         for (int s = 0; s < 4; ++s)
; #pragma unroll
;             for (int j = 0; j < 2; ++j) {
;                 u32x4 pw; pw.x = cvtpk(S[s][8 * j + 0], S[s][8 * j + 1]); pw.y = cvtpk(S[s][8 * j + 2], S[s][8 * j + 3]); pw.z = cvtpk(S[s][8 * j + 4], S[s][8 * j + 5]); pw.w = cvtpk(S[s][8 * j + 6], S[s][8 * j + 7]);
;                 const bf16x8 pf = __builtin_bit_cast(bf16x8, pw);
; #pragma unroll
;                 for (int d = 0; d < 4; ++d) {
;                     const LAS unsigned char* vp = Vts + (32 * d + r32) * VT_STRIDE + (128 * hf + 32 * s + 16 * j + 4 * hi) * 2;
;                     const s16x4 lo = *(const LAS s16x4*)vp, h4 = *(const LAS s16x4*)(vp + 16);
;                     const bf16x8 vf = __builtin_shufflevector(lo, h4, 0, 1, 2, 3, 4, 5, 6, 7);
;                     O[d] = MFMA32(vf, pf, O[d]);
;                 }
;                 __builtin_amdgcn_sched_barrier(0);
	v_add_f32_e32 v69, v122, v69
	v_exp_f32_e32 v91, v70
	v_fma_f32 v70, v96, s87, -v68
	v_add_f32_e32 v69, v127, v69
	v_exp_f32_e32 v96, v70
	v_fma_f32 v70, v112, s87, -v68
	v_add_f32_e32 v69, v86, v69
	v_exp_f32_e32 v112, v70
	v_fma_f32 v70, v106, s87, -v68
	v_add_f32_e32 v69, v88, v69
	v_exp_f32_e32 v106, v70
	v_fma_f32 v70, v85, s87, -v68
	v_add_f32_e32 v69, v91, v69
	v_exp_f32_e32 v119, v70
	v_fma_f32 v70, v84, s87, -v68
	v_add_f32_e32 v69, v96, v69
	v_exp_f32_e32 v124, v70
	v_add_f32_e32 v69, v112, v69
	v_add_f32_e32 v69, v106, v69
	v_add_f32_e32 v69, v119, v69
	v_exp_f32_e32 v85, v64
	v_fma_f32 v64, v65, s87, -v68
	v_add_f32_e32 v84, v124, v69
	v_exp_f32_e32 v69, v64
	v_fma_f32 v64, v66, s87, -v68
	v_exp_f32_e32 v70, v64
	v_fma_f32 v64, v67, s87, -v68
	v_exp_f32_e32 v71, v64
	v_fma_f32 v64, v80, s87, -v68
	v_exp_f32_e32 v72, v64
	v_fma_f32 v64, v81, s87, -v68
	v_exp_f32_e32 v73, v64
	v_fma_f32 v64, v82, s87, -v68
	v_exp_f32_e32 v74, v64
	v_fma_f32 v64, v83, s87, -v68
	v_exp_f32_e32 v75, v64
	v_fma_f32 v64, v99, s87, -v68
	v_lshl_add_u32 v99, s15, 8, v170
	ds_read2_b64 v[178:181], v99 offset1:2
	v_exp_f32_e32 v76, v64
	v_fma_f32 v64, v100, s87, -v68
	v_exp_f32_e32 v77, v64
	v_fma_f32 v64, v102, s87, -v68
	v_exp_f32_e32 v78, v64
	v_fma_f32 v64, v104, s87, -v68
	v_exp_f32_e32 v79, v64
	v_fma_f32 v64, v107, s87, -v68
	v_exp_f32_e32 v80, v64
	v_fma_f32 v64, v109, s87, -v68
	v_exp_f32_e32 v81, v64
	v_fma_f32 v64, v110, s87, -v68
	v_exp_f32_e32 v82, v64
	v_fma_f32 v64, v113, s87, -v68
	v_exp_f32_e32 v83, v64
	v_cvt_pk_bf16_f32 v64, v182, v183
	v_cvt_pk_bf16_f32 v65, v198, v184
	v_cvt_pk_bf16_f32 v66, v199, v185
	v_cvt_pk_bf16_f32 v67, v186, v187
	v_add_u32_e32 v100, 0x4000, v99
	v_add_u32_e32 v102, 0x8000, v99
	s_waitcnt lgkmcnt(0)
	v_mfma_f32_32x32x16_bf16 v[48:63], v[178:181], v[64:67], v[48:63]
	ds_read2_b64 v[178:181], v100 offset0:64 offset1:66
	v_add_u32_e32 v104, 0xc000, v99
	s_waitcnt lgkmcnt(0)
	v_mfma_f32_32x32x16_bf16 v[32:47], v[178:181], v[64:67], v[32:47]
	ds_read2_b64 v[178:181], v102 offset0:128 offset1:130
	s_waitcnt lgkmcnt(0)
	v_mfma_f32_32x32x16_bf16 v[16:31], v[178:181], v[64:67], v[16:31]
	ds_read2_b64 v[178:181], v104 offset0:192 offset1:194
	s_waitcnt lgkmcnt(0)
	v_mfma_f32_32x32x16_bf16 v[0:15], v[178:181], v[64:67], v[0:15]
	v_cvt_pk_bf16_f32 v67, v174, v176
	ds_read2_b64 v[176:179], v99 offset0:4 offset1:6
	v_cvt_pk_bf16_f32 v64, v95, v103
	v_cvt_pk_bf16_f32 v65, v111, v116
	v_cvt_pk_bf16_f32 v66, v123, v171
	s_waitcnt lgkmcnt(0)
	s_nop 0
	v_mfma_f32_32x32x16_bf16 v[48:63], v[176:179], v[64:67], v[48:63]
	ds_read2_b64 v[176:179], v100 offset0:68 offset1:70
	s_waitcnt lgkmcnt(0)
	v_mfma_f32_32x32x16_bf16 v[32:47], v[176:179], v[64:67], v[32:47]
	ds_read2_b64 v[176:179], v102 offset0:132 offset1:134
	s_waitcnt lgkmcnt(0)
	v_mfma_f32_32x32x16_bf16 v[16:31], v[176:179], v[64:67], v[16:31]
	ds_read2_b64 v[176:179], v104 offset0:196 offset1:198
	s_waitcnt lgkmcnt(0)
	v_mfma_f32_32x32x16_bf16 v[0:15], v[176:179], v[64:67], v[0:15]
	v_cvt_pk_bf16_f32 v67, v172, v175
	ds_read2_b64 v[174:177], v99 offset0:8 offset1:10
	v_cvt_pk_bf16_f32 v64, v92, v97
	v_cvt_pk_bf16_f32 v65, v105, v114
	v_cvt_pk_bf16_f32 v66, v120, v125
	s_waitcnt lgkmcnt(0)
	s_nop 0
	v_mfma_f32_32x32x16_bf16 v[48:63], v[174:177], v[64:67], v[48:63]
	ds_read2_b64 v[174:177], v100 offset0:72 offset1:74
	s_waitcnt lgkmcnt(0)
	v_mfma_f32_32x32x16_bf16 v[32:47], v[174:177], v[64:67], v[32:47]
	ds_read2_b64 v[174:177], v102 offset0:136 offset1:138
	s_waitcnt lgkmcnt(0)
	v_mfma_f32_32x32x16_bf16 v[16:31], v[174:177], v[64:67], v[16:31]
	ds_read2_b64 v[174:177], v104 offset0:200 offset1:202
	s_waitcnt lgkmcnt(0)
	v_mfma_f32_32x32x16_bf16 v[0:15], v[174:177], v[64:67], v[0:15]
	v_cvt_pk_bf16_f32 v65, v98, v108
	ds_read2_b64 v[108:111], v99 offset0:12 offset1:14
	v_cvt_pk_bf16_f32 v64, v89, v93
	v_cvt_pk_bf16_f32 v66, v117, v121
	v_cvt_pk_bf16_f32 v67, v126, v173
	s_waitcnt lgkmcnt(0)
	s_nop 0
	v_mfma_f32_32x32x16_bf16 v[48:63], v[108:111], v[64:67], v[48:63]
	ds_read2_b64 v[108:111], v100 offset0:76 offset1:78
	s_waitcnt lgkmcnt(0)
; #define LAS __attribute__((address_space(3)))
; __device__ __forceinline__ unsigned cvtpk(float lo, float hi) { f32x2 v = {lo, hi}; bf16x2_t b = __builtin_convertvector(v, bf16x2_t); return __builtin_bit_cast(unsigned, b); }
; #define MFMA32(a, b, c) __builtin_amdgcn_mfma_f32_32x32x16_bf16((a), (b), (c), 0, 0, 0)
; template <bool CAUSAL>
; __device__ __forceinline__ void attn_tile(const LAS unsigned char* Ks, const LAS unsigned char* Vts, const bf16x8 (&qf)[8], int qi, int r32, int hi, f32x16 (&O)[4], float& m2, float& l) {
;     ...
;         for (int s = 0; s < 4; ++s)
; #pragma unroll
;             for (int j = 0; j < 2; ++j) {
;                 u32x4 pw; pw.x = cvtpk(S[s][8 * j + 0], S[s][8 * j + 1]); pw.y = cvtpk(S[s][8 * j + 2], S[s][8 * j + 3]); pw.z = cvtpk(S[s][8 * j + 4], S[s][8 * j + 5]); pw.w = cvtpk(S[s][8 * j + 6], S[s][8 * j + 7]);
;                 const bf16x8 pf = __builtin_bit_cast(bf16x8, pw);
; #pragma unroll
;                 for (int d = 0; d < 4; ++d) {
;                     const LAS unsigned char* vp = Vts + (32 * d + r32) * VT_STRIDE + (128 * hf + 32 * s + 16 * j + 4 * hi) * 2;
;                     const s16x4 lo = *(const LAS s16x4*)vp, h4 = *(const LAS s16x4*)(vp + 16);
;                     const bf16x8 vf = __builtin_shufflevector(lo, h4, 0, 1, 2, 3, 4, 5, 6, 7);
;                     O[d] = MFMA32(vf, pf, O[d]);
;                 }
;                 __builtin_amdgcn_sched_barrier(0);
;             }
;     }
;     lsum += __shfl_xor(lsum, 32);
; __global__ void __launch_bounds__(512, 2) mk_fwd(Args a) {
;     ...
;                     const int nsel = b < 3 ? b : 3; const size_t pi = ((size_t)h * SEQ + tok) * 3;
;                     float M = m2;
; #pragma unroll 1
;                     for (int t = 0; t < nsel; ++t) M = fmaxf(M, ML[pi + t].x);
	v_mfma_f32_32x32x16_bf16 v[32:47], v[108:111], v[64:67], v[32:47]
	ds_read2_b64 v[108:111], v102 offset0:140 offset1:142
	s_waitcnt lgkmcnt(0)
	v_mfma_f32_32x32x16_bf16 v[16:31], v[108:111], v[64:67], v[16:31]
	ds_read2_b64 v[108:111], v104 offset0:204 offset1:206
	s_waitcnt lgkmcnt(0)
	v_mfma_f32_32x32x16_bf16 v[0:15], v[108:111], v[64:67], v[0:15]
	v_cvt_pk_bf16_f32 v65, v94, v101
	ds_read2_b64 v[92:95], v99 offset0:16 offset1:18
	v_cvt_pk_bf16_f32 v64, v87, v90
	v_cvt_pk_bf16_f32 v66, v115, v118
	v_cvt_pk_bf16_f32 v67, v122, v127
	s_waitcnt lgkmcnt(0)
	s_nop 0
	v_mfma_f32_32x32x16_bf16 v[48:63], v[92:95], v[64:67], v[48:63]
	ds_read2_b64 v[92:95], v100 offset0:80 offset1:82
	s_waitcnt lgkmcnt(0)
	v_mfma_f32_32x32x16_bf16 v[32:47], v[92:95], v[64:67], v[32:47]
	ds_read2_b64 v[92:95], v102 offset0:144 offset1:146
	s_waitcnt lgkmcnt(0)
	v_mfma_f32_32x32x16_bf16 v[16:31], v[92:95], v[64:67], v[16:31]
	ds_read2_b64 v[92:95], v104 offset0:208 offset1:210
	s_waitcnt lgkmcnt(0)
	v_mfma_f32_32x32x16_bf16 v[0:15], v[92:95], v[64:67], v[0:15]
	v_cvt_pk_bf16_f32 v64, v86, v88
	ds_read2_b64 v[86:89], v99 offset0:20 offset1:22
	v_cvt_pk_bf16_f32 v65, v91, v96
	v_cvt_pk_bf16_f32 v66, v112, v106
	v_cvt_pk_bf16_f32 v67, v119, v124
	s_waitcnt lgkmcnt(0)
	s_nop 0
	v_mfma_f32_32x32x16_bf16 v[48:63], v[86:89], v[64:67], v[48:63]
	ds_read2_b64 v[86:89], v100 offset0:84 offset1:86
	s_waitcnt lgkmcnt(0)
	v_mfma_f32_32x32x16_bf16 v[32:47], v[86:89], v[64:67], v[32:47]
	ds_read2_b64 v[86:89], v102 offset0:148 offset1:150
	s_waitcnt lgkmcnt(0)
	v_mfma_f32_32x32x16_bf16 v[16:31], v[86:89], v[64:67], v[16:31]
	ds_read2_b64 v[86:89], v104 offset0:212 offset1:214
	s_waitcnt lgkmcnt(0)
	v_mfma_f32_32x32x16_bf16 v[0:15], v[86:89], v[64:67], v[0:15]
	ds_read2_b64 v[64:67], v99 offset0:24 offset1:26
	v_cvt_pk_bf16_f32 v86, v85, v69
	v_cvt_pk_bf16_f32 v87, v70, v71
	v_cvt_pk_bf16_f32 v88, v72, v73
	v_cvt_pk_bf16_f32 v89, v74, v75
	s_waitcnt lgkmcnt(0)
	s_nop 0
	v_mfma_f32_32x32x16_bf16 v[48:63], v[64:67], v[86:89], v[48:63]
	ds_read2_b64 v[64:67], v100 offset0:88 offset1:90
	s_waitcnt lgkmcnt(0)
	v_mfma_f32_32x32x16_bf16 v[32:47], v[64:67], v[86:89], v[32:47]
	ds_read2_b64 v[64:67], v102 offset0:152 offset1:154
	s_waitcnt lgkmcnt(0)
	v_mfma_f32_32x32x16_bf16 v[16:31], v[64:67], v[86:89], v[16:31]
	ds_read2_b64 v[64:67], v104 offset0:216 offset1:218
	s_waitcnt lgkmcnt(0)
	v_mfma_f32_32x32x16_bf16 v[0:15], v[64:67], v[86:89], v[0:15]
	ds_read2_b64 v[64:67], v99 offset0:28 offset1:30
	v_cvt_pk_bf16_f32 v86, v76, v77
	v_cvt_pk_bf16_f32 v87, v78, v79
	v_cvt_pk_bf16_f32 v88, v80, v81
	v_cvt_pk_bf16_f32 v89, v82, v83
	s_waitcnt lgkmcnt(0)
	s_nop 0
	v_mfma_f32_32x32x16_bf16 v[48:63], v[64:67], v[86:89], v[48:63]
	ds_read2_b64 v[64:67], v100 offset0:92 offset1:94
	s_waitcnt lgkmcnt(0)
	v_mfma_f32_32x32x16_bf16 v[32:47], v[64:67], v[86:89], v[32:47]
	ds_read2_b64 v[64:67], v102 offset0:156 offset1:158
	s_waitcnt lgkmcnt(0)
	v_mfma_f32_32x32x16_bf16 v[16:31], v[64:67], v[86:89], v[16:31]
	ds_read2_b64 v[64:67], v104 offset0:220 offset1:222
	s_waitcnt lgkmcnt(0)
	v_mfma_f32_32x32x16_bf16 v[0:15], v[64:67], v[86:89], v[0:15]
	v_add_f32_e32 v64, v85, v84
	v_add_f32_e32 v64, v69, v64
	v_add_f32_e32 v64, v70, v64
	v_add_f32_e32 v64, v71, v64
	v_add_f32_e32 v64, v72, v64
	v_add_f32_e32 v64, v73, v64
	v_add_f32_e32 v64, v74, v64
	v_add_f32_e32 v64, v75, v64
	v_add_f32_e32 v64, v76, v64
	v_add_f32_e32 v64, v77, v64
	v_add_f32_e32 v64, v78, v64
	v_add_f32_e32 v64, v79, v64
	v_add_f32_e32 v64, v80, v64
	v_add_f32_e32 v64, v81, v64
	v_add_f32_e32 v64, v82, v64
	s_mov_b32 s15, 1
	s_and_b64 vcc, exec, s[0:1]
	s_mov_b64 s[0:1], 0
	v_add_f32_e32 v171, v83, v64
	s_cbranch_vccnz .LBB0_23
	ds_bpermute_b32 v66, v169, v171
	s_and_b32 s17, s6, 7
	s_min_i32 s15, s14, 3
	s_cmp_gt_i32 s14, 0
	s_mul_i32 s16, s17, 0x60000
	s_cselect_b64 s[0:1], -1, 0
	s_cmp_lt_i32 s14, 1
	v_mov_b32_e32 v69, v68
	s_cbranch_scc1 .LBB0_27
	s_add_u32 s18, s30, s16
	s_addc_u32 s19, s31, 0
	v_mad_i64_i32 v[64:65], s[18:19], v164, 24, s[18:19]
	s_mov_b32 s14, s15
	v_mov_b32_e32 v69, v68
